# attention: first eight V fragment reads of a tile hoisted into the QK MFMA block (free VGPRs)
# speedup vs baseline: 1.0044x; 1.0044x over previous
.LBB0_1107:
	s_lshl_b32 s2, 1, s10
	v_and_b32_e32 v0, s2, v205
	v_cmp_ne_u32_e32 vcc, 0, v0
	s_or_b64 s[2:3], s[8:9], vcc
	v_cndmask_b32_e64 v0, 0, 1, s[2:3]
	v_cmp_ne_u32_e32 vcc, 0, v0
	s_cbranch_vccz .LBB0_1118
	s_lshl_b32 s24, s10, 6
	s_cmp_gt_i32 s24, s17
	s_cselect_b64 s[10:11], -1, 0
	s_cmp_eq_u32 s23, 2
	s_cselect_b64 s[12:13], -1, 0
	s_sub_i32 s5, s20, s24
	s_cmpk_gt_i32 s5, 0x1ff
	s_cselect_b64 s[26:27], -1, 0
	s_lshl_b32 s5, s21, 14
	v_add_u32_e32 v32, s5, v206
	ds_read_b128 v[0:3], v32
	ds_read_b128 v[4:7], v32 offset:512
	ds_read_b128 v[8:11], v32 offset:2048
	ds_read_b128 v[12:15], v32 offset:2560
	ds_read_b128 v[16:19], v32 offset:4096
	ds_read_b128 v[20:23], v32 offset:4608
	ds_read_b128 v[24:27], v32 offset:6144
	ds_read_b128 v[28:31], v32 offset:6656
	s_waitcnt lgkmcnt(0)
	v_mfma_f32_32x32x16_bf16 v[114:129], v[0:3], v[130:133], 0
	s_and_b64 s[12:13], s[12:13], s[26:27]
	s_or_b64 s[10:11], s[10:11], s[12:13]
	s_mov_b64 s[12:13], -1
	s_andn2_b64 vcc, exec, s[10:11]
	v_mfma_f32_32x32x16_bf16 v[98:113], v[4:7], v[130:133], 0
	ds_read_b128 v[0:3], v32 offset:8192
	ds_read_b128 v[4:7], v32 offset:8704
	v_mfma_f32_32x32x16_bf16 v[114:129], v[8:11], v[134:137], v[114:129]
	v_mfma_f32_32x32x16_bf16 v[98:113], v[12:15], v[134:137], v[98:113]
	ds_read_b128 v[8:11], v32 offset:10240
	ds_read_b128 v[12:15], v32 offset:10752
	v_mfma_f32_32x32x16_bf16 v[114:129], v[16:19], v[138:141], v[114:129]
	v_mfma_f32_32x32x16_bf16 v[98:113], v[20:23], v[138:141], v[98:113]
	ds_read_b128 v[16:19], v32 offset:12288
	ds_read_b128 v[20:23], v32 offset:12800
	v_mfma_f32_32x32x16_bf16 v[114:129], v[24:27], v[142:145], v[114:129]
	v_mfma_f32_32x32x16_bf16 v[98:113], v[28:31], v[142:145], v[98:113]
	ds_read_b128 v[24:27], v32 offset:14336
	ds_read_b128 v[28:31], v32 offset:14848
	v_add_u32_e32 v252, s5, v169
	ds_read_b128 v[212:215], v252 offset:32768
	ds_read_b128 v[216:219], v252 offset:33280
	ds_read_b128 v[220:223], v252 offset:33792
	ds_read_b128 v[224:227], v252 offset:34304
	ds_read_b128 v[236:239], v252 offset:36864
	ds_read_b128 v[240:243], v252 offset:37376
	ds_read_b128 v[244:247], v252 offset:37888
	ds_read_b128 v[248:251], v252 offset:38400
	s_waitcnt lgkmcnt(8)
	v_mfma_f32_32x32x16_bf16 v[114:129], v[0:3], v[146:149], v[114:129]
	v_mfma_f32_32x32x16_bf16 v[98:113], v[4:7], v[146:149], v[98:113]
	v_mfma_f32_32x32x16_bf16 v[114:129], v[8:11], v[150:153], v[114:129]
	v_mfma_f32_32x32x16_bf16 v[98:113], v[12:15], v[150:153], v[98:113]
	v_mfma_f32_32x32x16_bf16 v[114:129], v[16:19], v[154:157], v[114:129]
	v_mfma_f32_32x32x16_bf16 v[98:113], v[20:23], v[154:157], v[98:113]
	v_mfma_f32_32x32x16_bf16 v[114:129], v[24:27], v[158:161], v[114:129]
	v_mfma_f32_32x32x16_bf16 v[98:113], v[28:31], v[158:161], v[98:113]
	s_cbranch_vccz .LBB0_1116
	s_nop 9
	v_max3_f32 v0, v114, s94, v115
	v_max3_f32 v0, v0, v116, v117
	v_max3_f32 v0, v0, v118, v119
	v_max3_f32 v0, v0, v120, v121
	v_max3_f32 v0, v0, v122, v123
	v_max3_f32 v0, v0, v124, v125
	v_max3_f32 v0, v0, v126, v127
	v_max3_f32 v0, v0, v128, v129
	v_max3_f32 v0, v0, v98, v99
	v_max3_f32 v0, v0, v100, v101
	v_max3_f32 v0, v0, v102, v103
	v_max3_f32 v0, v0, v104, v105
	v_max3_f32 v0, v0, v106, v107
	v_max3_f32 v0, v0, v108, v109
	v_max3_f32 v0, v0, v110, v111
	v_max3_f32 v0, v0, v112, v113
	ds_bpermute_b32 v1, v168, v0
	v_cndmask_b32_e64 v2, v233, v204, s[2:3]
	v_max_f32_e32 v3, v209, v209
	s_waitcnt lgkmcnt(0)
	v_max_f32_e32 v1, v1, v1
	v_max_f32_e32 v0, v0, v1
	v_add_f32_e32 v0, v2, v0
	v_max_f32_e32 v210, v3, v0
	v_sub_f32_e32 v167, v2, v210
	v_add_f32_e32 v0, v114, v167
	v_add_f32_e32 v1, v115, v167
	v_exp_f32_e32 v0, v0
	v_exp_f32_e32 v1, v1
	v_add_f32_e32 v2, v116, v167
	v_exp_f32_e32 v2, v2
	v_add_f32_e32 v3, v117, v167
	v_exp_f32_e32 v3, v3
	v_add_f32_e32 v4, 0, v0
	v_add_f32_e32 v4, v1, v4
	v_add_f32_e32 v4, v2, v4
	v_add_f32_e32 v8, v3, v4
	v_add_f32_e32 v4, v118, v167
	v_exp_f32_e32 v4, v4
	v_add_f32_e32 v5, v119, v167
	v_exp_f32_e32 v5, v5
	v_add_f32_e32 v6, v120, v167
	v_exp_f32_e32 v6, v6
	v_add_f32_e32 v7, v121, v167
	v_exp_f32_e32 v7, v7
	v_add_f32_e32 v8, v4, v8
	v_add_f32_e32 v8, v5, v8
	v_add_f32_e32 v8, v6, v8
	v_add_f32_e32 v12, v7, v8
	v_add_f32_e32 v8, v122, v167
	v_exp_f32_e32 v8, v8
	v_add_f32_e32 v9, v123, v167
	v_exp_f32_e32 v9, v9
	v_add_f32_e32 v10, v124, v167
	v_exp_f32_e32 v10, v10
	v_add_f32_e32 v11, v125, v167
	v_exp_f32_e32 v11, v11
	v_add_f32_e32 v12, v8, v12
	v_add_f32_e32 v12, v9, v12
	v_add_f32_e32 v12, v10, v12
	v_add_f32_e32 v16, v11, v12
	v_add_f32_e32 v12, v126, v167
	v_exp_f32_e32 v12, v12
	v_add_f32_e32 v13, v127, v167
	v_exp_f32_e32 v13, v13
	v_add_f32_e32 v14, v128, v167
	v_exp_f32_e32 v14, v14
	v_add_f32_e32 v15, v129, v167
	v_exp_f32_e32 v15, v15
	v_add_f32_e32 v16, v12, v16
	v_add_f32_e32 v16, v13, v16
	v_add_f32_e32 v16, v14, v16
	v_add_f32_e32 v20, v15, v16
	v_add_f32_e32 v16, v98, v167
	v_exp_f32_e32 v16, v16
	v_add_f32_e32 v17, v99, v167
	v_exp_f32_e32 v17, v17
	v_add_f32_e32 v18, v100, v167
	v_exp_f32_e32 v18, v18
	v_add_f32_e32 v19, v101, v167
	v_exp_f32_e32 v19, v19
	v_add_f32_e32 v20, v16, v20
	v_add_f32_e32 v20, v17, v20
	v_add_f32_e32 v20, v18, v20
	v_add_f32_e32 v24, v19, v20
	v_add_f32_e32 v20, v102, v167
	v_exp_f32_e32 v20, v20
	v_add_f32_e32 v21, v103, v167
	v_exp_f32_e32 v21, v21
	v_add_f32_e32 v22, v104, v167
	v_exp_f32_e32 v22, v22
	v_add_f32_e32 v23, v105, v167
	v_exp_f32_e32 v23, v23
	v_add_f32_e32 v24, v20, v24
	v_add_f32_e32 v24, v21, v24
	v_add_f32_e32 v24, v22, v24
	v_add_f32_e32 v28, v23, v24
	v_add_f32_e32 v24, v106, v167
	v_exp_f32_e32 v24, v24
	v_add_f32_e32 v25, v107, v167
	v_exp_f32_e32 v25, v25
	v_add_f32_e32 v26, v108, v167
	v_exp_f32_e32 v26, v26
	v_add_f32_e32 v27, v109, v167
	v_exp_f32_e32 v27, v27
	v_add_f32_e32 v28, v24, v28
	v_add_f32_e32 v28, v25, v28
	v_add_f32_e32 v28, v26, v28
	v_add_f32_e32 v31, v27, v28
	v_add_f32_e32 v28, v110, v167
	v_exp_f32_e32 v28, v28
	v_add_f32_e32 v29, v111, v167
	v_exp_f32_e32 v29, v29
	v_add_f32_e32 v30, v112, v167
	v_exp_f32_e32 v30, v30
	v_add_f32_e32 v31, v28, v31
	v_add_f32_e32 v166, v29, v31
	v_mov_b32_e32 v31, v113
	v_pk_add_f32 v[166:167], v[30:31], v[166:167]
	s_cbranch_execz .LBB0_1117

.LBB0_1112:
	v_exp_f32_e32 v31, v167
	v_cvt_pk_bf16_f32 v0, v0, v1
	v_cvt_pk_bf16_f32 v1, v2, v3
	v_cvt_pk_bf16_f32 v2, v4, v5
	v_add_f32_e32 v166, v31, v166
	v_fmac_f32_e32 v166, v208, v32
	v_add_u32_e32 v32, s5, v169
	v_cvt_pk_bf16_f32 v3, v6, v7
	v_cvt_pk_bf16_f32 v8, v8, v9
	v_cvt_pk_bf16_f32 v9, v10, v11
	s_waitcnt lgkmcnt(0)
	v_mfma_f32_32x32x16_bf16 v[66:81], v[212:215], v[0:3], v[66:81]
	ds_read_b128 v[4:7], v32 offset:40960
	v_cvt_pk_bf16_f32 v10, v12, v13
	v_cvt_pk_bf16_f32 v11, v14, v15
	v_cvt_pk_bf16_f32 v16, v16, v17
	v_cvt_pk_bf16_f32 v17, v18, v19
	v_cvt_pk_bf16_f32 v18, v20, v21
	v_cvt_pk_bf16_f32 v19, v22, v23
	v_mfma_f32_32x32x16_bf16 v[82:97], v[216:219], v[0:3], v[82:97]
	ds_read_b128 v[98:101], v32 offset:41472
	v_mov_b32_e32 v208, v166
	v_mfma_f32_32x32x16_bf16 v[50:65], v[220:223], v[0:3], v[50:65]
	ds_read_b128 v[102:105], v32 offset:41984
	v_mfma_f32_32x32x16_bf16 v[34:49], v[224:227], v[0:3], v[34:49]
	ds_read_b128 v[0:3], v32 offset:42496
	v_mfma_f32_32x32x16_bf16 v[66:81], v[236:239], v[8:11], v[66:81]
	ds_read_b128 v[12:15], v32 offset:45056
	v_mfma_f32_32x32x16_bf16 v[82:97], v[240:243], v[8:11], v[82:97]
	ds_read_b128 v[106:109], v32 offset:45568
	v_mfma_f32_32x32x16_bf16 v[50:65], v[244:247], v[8:11], v[50:65]
	ds_read_b128 v[110:113], v32 offset:46080
	v_mfma_f32_32x32x16_bf16 v[34:49], v[248:251], v[8:11], v[34:49]
	ds_read_b128 v[8:11], v32 offset:46592
	s_waitcnt lgkmcnt(0)
	v_mfma_f32_32x32x16_bf16 v[66:81], v[4:7], v[16:19], v[66:81]
	v_mfma_f32_32x32x16_bf16 v[82:97], v[98:101], v[16:19], v[82:97]
	v_mfma_f32_32x32x16_bf16 v[50:65], v[102:105], v[16:19], v[50:65]
	v_mfma_f32_32x32x16_bf16 v[34:49], v[0:3], v[16:19], v[34:49]
	v_cvt_pk_bf16_f32 v0, v24, v25
	v_cvt_pk_bf16_f32 v1, v26, v27
	v_cvt_pk_bf16_f32 v2, v28, v29
	v_cvt_pk_bf16_f32 v3, v30, v31
	s_nop 1
	v_mfma_f32_32x32x16_bf16 v[66:81], v[12:15], v[0:3], v[66:81]
	v_mfma_f32_32x32x16_bf16 v[82:97], v[106:109], v[0:3], v[82:97]
	v_mfma_f32_32x32x16_bf16 v[50:65], v[110:113], v[0:3], v[50:65]
	v_mfma_f32_32x32x16_bf16 v[34:49], v[8:11], v[0:3], v[34:49]
	s_cmp_eq_u32 s22, s23
	s_cbranch_scc1 .LBB0_1119
